# pool trailing-sum loop: 8 LDS reads of an iteration issued up front (one exposed latency per 4 elements)
# speedup vs baseline: 1.0062x; 1.0062x over previous
; #define MFMA(a, b, c) __builtin_amdgcn_mfma_f32_32x32x16_bf16((a), (b), (c), 0, 0, 0)
; DI float bf2f(u16 v) { return __uint_as_float((unsigned)v << 16); }
; DI u16 f2bf(float x) { return (u16)(pk2(x, 0.f) & 0xffffu); }
; DI float lo16(unsigned w) { return __uint_as_float(w << 16); }
; DI float hi16(unsigned w) { return __uint_as_float(w & 0xffff0000u); }
; DI float siluf_(float x) { return x / (1.f + __expf(-x)); }
; DI void pool_item(const Params& p, int l, int it, char* lds) {
;     ...
;     const int ch = tid, w = 2 << g;
;     float s = 0.f;
;     for (int r = 17 - w; r <= 16; ++r) s += bf2f(cin[r * 256 + ch]);
; #pragma unroll 4
;     for (int i = 0; i < 32; ++i) {
;       const int t = q0 + i; const int cnt = (t + 1 < w) ? t + 1 : w;
;       const float self = bf2f(cin[(i + 16) * 256 + ch]);
;       *(u16*)(pl + i * 528 + ch * 2) = f2bf(s / (float)cnt - self);
;       s += bf2f(cin[(i + 17) * 256 + ch]) - bf2f(cin[(i + 17 - w) * 256 + ch]);
;     }
;   }
;   __syncthreads();
;   f32x16 acc[2];
; #pragma unroll
;   for (int r = 0; r < 16; ++r) { acc[0][r] = 0.f; acc[1][r] = 0.f; }
; #pragma unroll
;   for (int s4 = 0; s4 < 4; ++s4) {
;     const bf16x8 bf = *(const bf16x8*)(pl + l31 * 528 + (g * 64 + 16 * s4 + 8 * hi) * 2);
; #pragma unroll
;     for (int dt = 0; dt < 2; ++dt) acc[dt] = MFMA(af[s4 * 2 + dt], bf, acc[dt]);
;   }
;   u16* y = (u16*)(ws_ + OFF_XB);
; #pragma unroll
;   for (int dt = 0; dt < 2; ++dt)
; #pragma unroll
;     for (int g4 = 0; g4 < 4; ++g4) {
;       const int col = g * 64 + dt * 32 + 8 * g4 + 4 * hi;
;       const f32x4 ps = psv[dt * 4 + g4];
;       const u32x2 z = zv[dt * 4 + g4];
;       u32x2 v;
;       v[0] = pk2(acc[dt][4 * g4] * ps[0] * siluf_(lo16(z[0])), acc[dt][4 * g4 + 1] * ps[1] * siluf_(hi16(z[0])));
;       v[1] = pk2(acc[dt][4 * g4 + 2] * ps[2] * siluf_(lo16(z[1])), acc[dt][4 * g4 + 3] * ps[3] * siluf_(hi16(z[1])));
;       *(u32x2*)(y + tok * 1024 + 512 + col) = v;
;     }
.LBB0_464:
	v_add_u32_e32 v16, v13, v10
	ds_read_u16 v236, v16 offset:512
	ds_read_u16 v237, v13 offset:512
	ds_read_u16 v238, v16 offset:1024
	ds_read_u16 v239, v13 offset:1024
	ds_read_u16 v240, v16 offset:1536
	ds_read_u16 v241, v13 offset:1536
	ds_read_u16 v242, v16 offset:2048
	ds_read_u16 v243, v13 offset:2048
	v_add_u32_e32 v15, s2, v118
	s_add_i32 s2, s2, 4
	v_add_u32_e32 v16, 1, v15
	v_min_i32_e32 v16, v16, v9
	v_cvt_f32_i32_e32 v16, v16
	s_waitcnt lgkmcnt(0)
	v_lshlrev_b32_e32 v14, 16, v14
	v_rcp_f32_e32 v17, v16
	s_nop 0
	v_mul_f32_e32 v16, v12, v17
	v_sub_f32_e32 v16, v16, v14
	v_cvt_pk_bf16_f32 v16, v16, s0
	ds_write_b16 v11, v16
	v_lshlrev_b32_e32 v236, 16, v236
	v_lshlrev_b32_e32 v237, 16, v237
	v_sub_f32_e32 v16, v237, v236
	v_add_f32_e32 v12, v12, v16
	v_add_u32_e32 v16, 2, v15
	v_min_i32_e32 v16, v16, v9
	v_cvt_f32_i32_e32 v16, v16
	v_rcp_f32_e32 v17, v16
	s_nop 0
	v_mul_f32_e32 v16, v12, v17
	v_sub_f32_e32 v16, v16, v237
	v_cvt_pk_bf16_f32 v16, v16, s0
	ds_write_b16 v11, v16 offset:528
	v_lshlrev_b32_e32 v238, 16, v238
	v_lshlrev_b32_e32 v239, 16, v239
	v_sub_f32_e32 v16, v239, v238
	v_add_f32_e32 v12, v12, v16
	v_add_u32_e32 v16, 3, v15
	v_min_i32_e32 v16, v16, v9
	v_cvt_f32_i32_e32 v16, v16
	v_rcp_f32_e32 v17, v16
	s_nop 0
	v_mul_f32_e32 v16, v12, v17
	v_sub_f32_e32 v16, v16, v239
	v_cvt_pk_bf16_f32 v16, v16, s0
	ds_write_b16 v11, v16 offset:1056
	v_lshlrev_b32_e32 v240, 16, v240
	v_lshlrev_b32_e32 v241, 16, v241
	v_sub_f32_e32 v16, v241, v240
	v_add_f32_e32 v12, v12, v16
	v_add_u32_e32 v16, 4, v15
	v_min_i32_e32 v16, v16, v9
	v_cvt_f32_i32_e32 v16, v16
	v_rcp_f32_e32 v17, v16
	s_nop 0
	v_mul_f32_e32 v16, v12, v17
	v_sub_f32_e32 v16, v16, v241
	v_cvt_pk_bf16_f32 v16, v16, s0
	ds_write_b16 v11, v16 offset:1584
	v_lshlrev_b32_e32 v242, 16, v242
	v_lshlrev_b32_e32 v16, 16, v243
	v_sub_f32_e32 v16, v16, v242
	v_add_f32_e32 v12, v12, v16
	v_mov_b32_e32 v14, v243
	v_add_u32_e32 v13, 0x800, v13
	v_add_u32_e32 v11, 0x840, v11
	s_cmp_lg_u32 s2, 32
	s_cbranch_scc1 .LBB0_464
	v_mul_u32_u24_e32 v9, 0x210, v120
	v_and_b32_e32 v8, 0xffffff80, v8
	v_add3_u32 v124, v9, v178, v8
	s_barrier
	ds_read_b128 v[8:11], v124 offset:24576
	ds_read_b128 v[120:123], v124 offset:24608
	s_waitcnt vmcnt(23) lgkmcnt(1)
	v_mfma_f32_32x32x16_bf16 v[16:31], v[0:3], v[8:11], 0
	v_mov_b32_e32 v183, v179
	s_mov_b64 s[2:3], 0xd390000
	v_mov_b32_e32 v185, v179
	s_mov_b64 s[4:5], 0x8000
	v_add_u32_e32 v118, 32, v118
	s_waitcnt vmcnt(22)
	v_mfma_f32_32x32x16_bf16 v[0:15], v[4:7], v[8:11], 0
	s_waitcnt vmcnt(21) lgkmcnt(0)
	v_mfma_f32_32x32x16_bf16 v[16:31], v[76:79], v[120:123], v[16:31]
	ds_read_b128 v[76:79], v124 offset:24640
	s_waitcnt vmcnt(19)
	v_mfma_f32_32x32x16_bf16 v[0:15], v[84:87], v[120:123], v[0:15]
	s_waitcnt lgkmcnt(0)
	v_mfma_f32_32x32x16_bf16 v[16:31], v[64:67], v[76:79], v[16:31]
	ds_read_b128 v[64:67], v124 offset:24672
	s_waitcnt vmcnt(18)
	v_mfma_f32_32x32x16_bf16 v[0:15], v[80:83], v[76:79], v[0:15]
	s_waitcnt vmcnt(17) lgkmcnt(0)
	v_mfma_f32_32x32x16_bf16 v[16:31], v[68:71], v[64:67], v[16:31]
	s_waitcnt vmcnt(11)
	v_lshlrev_b32_e32 v68, 16, v112
	v_and_b32_e32 v69, 0xffff0000, v112
	v_mfma_f32_32x32x16_bf16 v[0:15], v[72:75], v[64:67], v[0:15]
	v_mul_f32_e32 v66, 0xbfb8aa3b, v68
	s_nop 6
	v_mul_f32_e64 v16, v60, v16
	v_mul_f32_e64 v17, v61, v17
	v_mul_f32_e32 v60, 0xbfb8aa3b, v69
	v_exp_f32_e32 v66, v66
	v_exp_f32_e32 v67, v60
	v_lshlrev_b64 v[64:65], 11, v[114:115]
	v_lshl_add_u64 v[64:65], s[0:1], 0, v[64:65]
	s_mov_b64 s[0:1], 0x2a40400
	v_pk_add_f32 v[60:61], v[66:67], 1.0 op_sel_hi:[1,0]
	v_lshl_add_u64 v[64:65], v[64:65], 0, s[0:1]
	v_pk_mul_f32 v[18:19], v[62:63], v[18:19]
	v_pk_mul_f32 v[20:21], v[56:57], v[20:21]
	v_pk_mul_f32 v[22:23], v[58:59], v[22:23]
	v_rcp_f32_e32 v61, v61
	s_nop 0
	v_mul_f32_e32 v61, v69, v61
	s_waitcnt vmcnt(7)
	v_pk_mul_f32 v[0:1], v[44:45], v[0:1]
	v_pk_mul_f32 v[2:3], v[46:47], v[2:3]
	v_rcp_f32_e32 v60, v60
	s_nop 0
	v_mul_f32_e32 v60, v68, v60
	v_pk_mul_f32 v[16:17], v[60:61], v[16:17]
	v_lshlrev_b32_e32 v61, 16, v113
	v_and_b32_e32 v66, 0xffff0000, v113
	v_cvt_pk_bf16_f32 v60, v16, v17
	v_mul_f32_e32 v16, 0xbfb8aa3b, v61
	v_mul_f32_e32 v17, 0xbfb8aa3b, v66
	v_exp_f32_e32 v16, v16
	v_exp_f32_e32 v17, v17
	s_nop 0
	v_pk_add_f32 v[16:17], v[16:17], 1.0 op_sel_hi:[1,0]
	s_nop 0
	s_nop 0
	v_rcp_f32_e32 v17, v17
	s_nop 0
	v_mul_f32_e32 v17, v66, v17
	s_nop 0
	v_rcp_f32_e32 v16, v16
	s_nop 0
	v_mul_f32_e32 v16, v61, v16
	v_pk_mul_f32 v[16:17], v[16:17], v[18:19]
	s_nop 0
	v_cvt_pk_bf16_f32 v61, v16, v17
	v_lshl_add_u64 v[16:17], v[110:111], 1, v[64:65]
	global_store_dwordx2 v[16:17], v[60:61], off
	v_lshlrev_b32_e32 v60, 16, v108
	v_and_b32_e32 v61, 0xffff0000, v108
	v_mul_f32_e32 v18, 0xbfb8aa3b, v60
	v_mul_f32_e32 v19, 0xbfb8aa3b, v61
	v_exp_f32_e32 v18, v18
	v_exp_f32_e32 v19, v19
	s_nop 0
	v_pk_add_f32 v[18:19], v[18:19], 1.0 op_sel_hi:[1,0]
	s_nop 0
	s_nop 0
	v_rcp_f32_e32 v19, v19
	s_nop 0
	v_mul_f32_e32 v19, v61, v19
	s_nop 0
	v_rcp_f32_e32 v18, v18
	s_nop 0
	v_mul_f32_e32 v18, v60, v18
	v_pk_mul_f32 v[18:19], v[18:19], v[20:21]
	v_and_b32_e32 v56, 0xffff0000, v109
	v_cvt_pk_bf16_f32 v18, v18, v19
	v_lshlrev_b32_e32 v19, 16, v109
	v_mul_f32_e32 v20, 0xbfb8aa3b, v19
	v_mul_f32_e32 v21, 0xbfb8aa3b, v56
	v_exp_f32_e32 v20, v20
	v_exp_f32_e32 v21, v21
	s_nop 0
	v_pk_add_f32 v[20:21], v[20:21], 1.0 op_sel_hi:[1,0]
	s_nop 0
	s_nop 0
	v_rcp_f32_e32 v21, v21
	s_nop 0
	v_mul_f32_e32 v21, v56, v21
	s_nop 0
	v_rcp_f32_e32 v20, v20
	s_nop 0
	v_mul_f32_e32 v20, v19, v20
	v_pk_mul_f32 v[20:21], v[20:21], v[22:23]
	v_lshlrev_b32_e32 v22, 16, v104
	v_cvt_pk_bf16_f32 v19, v20, v21
	v_lshl_add_u64 v[20:21], v[106:107], 1, v[64:65]
; DI float lo16(unsigned w) { return __uint_as_float(w << 16); }
; DI float hi16(unsigned w) { return __uint_as_float(w & 0xffff0000u); }
; DI float siluf_(float x) { return x / (1.f + __expf(-x)); }
; DI void pool_item(const Params& p, int l, int it, char* lds) {
;     ...
; #pragma unroll
;   for (int dt = 0; dt < 2; ++dt)
; #pragma unroll
;     for (int g4 = 0; g4 < 4; ++g4) {
;       const int col = g * 64 + dt * 32 + 8 * g4 + 4 * hi;
;       const f32x4 ps = psv[dt * 4 + g4];
;       const u32x2 z = zv[dt * 4 + g4];
;       u32x2 v;
;       v[0] = pk2(acc[dt][4 * g4] * ps[0] * siluf_(lo16(z[0])), acc[dt][4 * g4 + 1] * ps[1] * siluf_(hi16(z[0])));
;       v[1] = pk2(acc[dt][4 * g4 + 2] * ps[2] * siluf_(lo16(z[1])), acc[dt][4 * g4 + 3] * ps[3] * siluf_(hi16(z[1])));
;       *(u32x2*)(y + tok * 1024 + 512 + col) = v;
;     }
	v_and_b32_e32 v23, 0xffff0000, v104
	global_store_dwordx2 v[20:21], v[18:19], off
	v_mul_f32_e32 v18, 0xbfb8aa3b, v22
	v_mul_f32_e32 v19, 0xbfb8aa3b, v23
	v_exp_f32_e32 v18, v18
	v_exp_f32_e32 v19, v19
	v_pk_mul_f32 v[20:21], v[52:53], v[24:25]
	v_pk_add_f32 v[18:19], v[18:19], 1.0 op_sel_hi:[1,0]
	s_nop 0
	s_nop 0
	v_rcp_f32_e32 v19, v19
	s_nop 0
	v_mul_f32_e32 v19, v23, v19
	s_nop 0
	v_rcp_f32_e32 v18, v18
	s_nop 0
	v_mul_f32_e32 v18, v22, v18
	v_pk_mul_f32 v[18:19], v[18:19], v[20:21]
	v_and_b32_e32 v24, 0xffff0000, v105
	v_cvt_pk_bf16_f32 v18, v18, v19
	v_lshlrev_b32_e32 v19, 16, v105
	v_mul_f32_e32 v20, 0xbfb8aa3b, v19
	v_mul_f32_e32 v21, 0xbfb8aa3b, v24
	v_exp_f32_e32 v20, v20
	v_exp_f32_e32 v21, v21
	v_pk_mul_f32 v[22:23], v[54:55], v[26:27]
	v_pk_add_f32 v[20:21], v[20:21], 1.0 op_sel_hi:[1,0]
	s_nop 0
	s_nop 0
	v_rcp_f32_e32 v21, v21
	s_nop 0
	v_mul_f32_e32 v21, v24, v21
	s_nop 0
	v_rcp_f32_e32 v20, v20
	s_nop 0
	v_mul_f32_e32 v20, v19, v20
	v_pk_mul_f32 v[20:21], v[20:21], v[22:23]
	v_lshlrev_b32_e32 v22, 16, v100
	v_cvt_pk_bf16_f32 v19, v20, v21
	v_lshl_add_u64 v[20:21], v[102:103], 1, v[64:65]
	v_and_b32_e32 v23, 0xffff0000, v100
	global_store_dwordx2 v[20:21], v[18:19], off
	v_mul_f32_e32 v18, 0xbfb8aa3b, v22
	v_mul_f32_e32 v19, 0xbfb8aa3b, v23
	v_exp_f32_e32 v18, v18
	v_exp_f32_e32 v19, v19
	v_pk_mul_f32 v[20:21], v[48:49], v[28:29]
	v_pk_add_f32 v[18:19], v[18:19], 1.0 op_sel_hi:[1,0]
	s_nop 0
	s_nop 0
	v_rcp_f32_e32 v19, v19
	s_nop 0
	v_mul_f32_e32 v19, v23, v19
	s_nop 0
	v_rcp_f32_e32 v18, v18
	s_nop 0
	v_mul_f32_e32 v18, v22, v18
	v_pk_mul_f32 v[18:19], v[18:19], v[20:21]
	v_and_b32_e32 v24, 0xffff0000, v101
	v_cvt_pk_bf16_f32 v18, v18, v19
	v_lshlrev_b32_e32 v19, 16, v101
	v_mul_f32_e32 v20, 0xbfb8aa3b, v19
	v_mul_f32_e32 v21, 0xbfb8aa3b, v24
	v_exp_f32_e32 v20, v20
	v_exp_f32_e32 v21, v21
	v_pk_mul_f32 v[22:23], v[50:51], v[30:31]
	v_pk_add_f32 v[20:21], v[20:21], 1.0 op_sel_hi:[1,0]
	s_nop 0
	s_nop 0
	v_rcp_f32_e32 v21, v21
	s_nop 0
	v_mul_f32_e32 v21, v24, v21
	s_nop 0
	v_rcp_f32_e32 v20, v20
	s_nop 0
	v_mul_f32_e32 v20, v19, v20
	v_pk_mul_f32 v[20:21], v[20:21], v[22:23]
	s_nop 0
	v_cvt_pk_bf16_f32 v19, v20, v21
	v_lshl_add_u64 v[20:21], v[98:99], 1, v[64:65]
	global_store_dwordx2 v[20:21], v[18:19], off
	s_waitcnt vmcnt(7)
	v_lshlrev_b32_e32 v20, 16, v96
	v_and_b32_e32 v21, 0xffff0000, v96
	v_mul_f32_e32 v18, 0xbfb8aa3b, v20
	v_mul_f32_e32 v19, 0xbfb8aa3b, v21
	v_exp_f32_e32 v18, v18
	v_exp_f32_e32 v19, v19
	s_nop 0
	v_pk_add_f32 v[18:19], v[18:19], 1.0 op_sel_hi:[1,0]
	s_nop 0
	s_nop 0
	v_rcp_f32_e32 v19, v19
	s_nop 0
	v_mul_f32_e32 v19, v21, v19
	s_nop 0
	v_rcp_f32_e32 v18, v18
	s_nop 0
	v_mul_f32_e32 v18, v20, v18
	v_pk_mul_f32 v[0:1], v[18:19], v[0:1]
	v_and_b32_e32 v20, 0xffff0000, v97
	v_cvt_pk_bf16_f32 v0, v0, v1
	v_lshlrev_b32_e32 v1, 16, v97
	v_mul_f32_e32 v18, 0xbfb8aa3b, v1
	v_mul_f32_e32 v19, 0xbfb8aa3b, v20
	v_exp_f32_e32 v18, v18
	v_exp_f32_e32 v19, v19
	s_nop 0
	v_pk_add_f32 v[18:19], v[18:19], 1.0 op_sel_hi:[1,0]
	s_nop 0
	s_nop 0
	v_rcp_f32_e32 v19, v19
	s_nop 0
	v_mul_f32_e32 v19, v20, v19
	s_nop 0
	v_rcp_f32_e32 v18, v18
	s_nop 0
	v_mul_f32_e32 v18, v1, v18
	v_pk_mul_f32 v[2:3], v[18:19], v[2:3]
	s_waitcnt vmcnt(6)
	v_lshlrev_b32_e32 v18, 16, v92
	v_cvt_pk_bf16_f32 v1, v2, v3
	v_lshl_add_u64 v[2:3], v[94:95], 1, v[64:65]
	v_and_b32_e32 v19, 0xffff0000, v92
	global_store_dwordx2 v[2:3], v[0:1], off
	v_mul_f32_e32 v0, 0xbfb8aa3b, v18
	v_mul_f32_e32 v1, 0xbfb8aa3b, v19
	v_exp_f32_e32 v0, v0
	v_exp_f32_e32 v1, v1
	v_pk_mul_f32 v[2:3], v[40:41], v[4:5]
	v_pk_add_f32 v[0:1], v[0:1], 1.0 op_sel_hi:[1,0]
	s_nop 0
	s_nop 0
	v_rcp_f32_e32 v1, v1
	s_nop 0
	v_mul_f32_e32 v1, v19, v1
	s_nop 0
	v_rcp_f32_e32 v0, v0
	s_nop 0
	v_mul_f32_e32 v0, v18, v0
	v_pk_mul_f32 v[0:1], v[0:1], v[2:3]
	v_and_b32_e32 v18, 0xffff0000, v93
	v_cvt_pk_bf16_f32 v0, v0, v1
	v_lshlrev_b32_e32 v1, 16, v93
	v_mul_f32_e32 v2, 0xbfb8aa3b, v1
	v_mul_f32_e32 v3, 0xbfb8aa3b, v18
	v_exp_f32_e32 v2, v2
	v_exp_f32_e32 v3, v3
	v_pk_mul_f32 v[4:5], v[42:43], v[6:7]
	v_pk_add_f32 v[2:3], v[2:3], 1.0 op_sel_hi:[1,0]
	s_nop 0
	s_nop 0
	v_rcp_f32_e32 v3, v3
	s_nop 0
	v_mul_f32_e32 v3, v18, v3
	s_nop 0
	v_rcp_f32_e32 v2, v2
	s_nop 0
	v_mul_f32_e32 v2, v1, v2
	v_pk_mul_f32 v[2:3], v[2:3], v[4:5]
	s_waitcnt vmcnt(6)
	v_lshlrev_b32_e32 v4, 16, v90
	v_cvt_pk_bf16_f32 v1, v2, v3
	v_and_b32_e32 v5, 0xffff0000, v90
	global_store_dwordx2 v[16:17], v[0:1], off offset:80
	v_mul_f32_e32 v0, 0xbfb8aa3b, v4
	v_mul_f32_e32 v1, 0xbfb8aa3b, v5
	v_exp_f32_e32 v0, v0
	v_exp_f32_e32 v1, v1
	v_pk_mul_f32 v[2:3], v[36:37], v[8:9]
	v_pk_add_f32 v[0:1], v[0:1], 1.0 op_sel_hi:[1,0]
	s_nop 0
	s_nop 0
	v_rcp_f32_e32 v1, v1
	s_nop 0
	v_mul_f32_e32 v1, v5, v1
	s_nop 0
	v_rcp_f32_e32 v0, v0
	s_nop 0
	v_mul_f32_e32 v0, v4, v0
	v_pk_mul_f32 v[0:1], v[0:1], v[2:3]
	v_and_b32_e32 v6, 0xffff0000, v91
	v_cvt_pk_bf16_f32 v0, v0, v1
	v_lshlrev_b32_e32 v1, 16, v91
	v_mul_f32_e32 v2, 0xbfb8aa3b, v1
	v_mul_f32_e32 v3, 0xbfb8aa3b, v6
	v_exp_f32_e32 v2, v2
	v_exp_f32_e32 v3, v3
	v_pk_mul_f32 v[4:5], v[38:39], v[10:11]
	v_pk_add_f32 v[2:3], v[2:3], 1.0 op_sel_hi:[1,0]
	s_nop 0
	s_nop 0
	v_rcp_f32_e32 v3, v3
	s_nop 0
	v_mul_f32_e32 v3, v6, v3
	s_nop 0
	v_rcp_f32_e32 v2, v2
	s_nop 0
	v_mul_f32_e32 v2, v1, v2
	v_pk_mul_f32 v[2:3], v[2:3], v[4:5]
	s_waitcnt vmcnt(6)
; DI void dilcomb_item(const Params& p, int it) {
;     ...
;   for (int i = 0; i < 4; ++i) {
;     const int idx = it * 1024 + i * 256 + threadIdx.x;
;     const size_t tok = idx >> 5; const int c8 = idx & 31, h = c8 >> 3;
;     const float l0 = lse[((size_t)0 * T_ + tok) * 4 + h], l1 = lse[((size_t)1 * T_ + tok) * 4 + h], l2 = lse[((size_t)2 * T_ + tok) * 4 + h];
;     const float mx = fmaxf(l0, fmaxf(l1, l2));
;     float w0 = __expf(l0 - mx), w1 = __expf(l1 - mx), w2 = __expf(l2 - mx);
;     const float iw = 1.f / (w0 + w1 + w2); w0 *= iw; w1 *= iw; w2 *= iw;
;     const u32x4 a = *(const u32x4*)(od + ((size_t)0 * T_ + tok) * 256 + c8 * 8), bq = *(const u32x4*)(od + ((size_t)1 * T_ + tok) * 256 + c8 * 8), cq = *(const u32x4*)(od + ((size_t)2 * T_ + tok) * 256 + c8 * 8);
;     const u32x4 z = *(const u32x4*)(proj + tok * NP + C_BZ + c8 * 8);
	v_lshlrev_b32_e32 v4, 16, v88
	v_cvt_pk_bf16_f32 v1, v2, v3
	v_and_b32_e32 v5, 0xffff0000, v88
	global_store_dwordx2 v[16:17], v[0:1], off offset:96
	v_mul_f32_e32 v0, 0xbfb8aa3b, v4
	v_mul_f32_e32 v1, 0xbfb8aa3b, v5
	v_exp_f32_e32 v0, v0
	v_exp_f32_e32 v1, v1
	v_pk_mul_f32 v[2:3], v[32:33], v[12:13]
	v_pk_add_f32 v[0:1], v[0:1], 1.0 op_sel_hi:[1,0]
	s_nop 0
	s_nop 0
	v_rcp_f32_e32 v1, v1
	s_nop 0
	v_mul_f32_e32 v1, v5, v1
	s_nop 0
	v_rcp_f32_e32 v0, v0
	s_nop 0
	v_mul_f32_e32 v0, v4, v0
	v_pk_mul_f32 v[0:1], v[0:1], v[2:3]
	v_and_b32_e32 v6, 0xffff0000, v89
	v_cvt_pk_bf16_f32 v0, v0, v1
	v_lshlrev_b32_e32 v1, 16, v89
	v_mul_f32_e32 v2, 0xbfb8aa3b, v1
	v_mul_f32_e32 v3, 0xbfb8aa3b, v6
	v_exp_f32_e32 v2, v2
	v_exp_f32_e32 v3, v3
	v_pk_mul_f32 v[4:5], v[34:35], v[14:15]
	v_pk_add_f32 v[2:3], v[2:3], 1.0 op_sel_hi:[1,0]
	s_nop 0
	s_nop 0
	v_rcp_f32_e32 v3, v3
	s_nop 0
	v_mul_f32_e32 v3, v6, v3
	s_mov_b64 s[0:1], 0
	v_rcp_f32_e32 v2, v2
	s_nop 0
	v_mul_f32_e32 v2, v1, v2
	v_pk_mul_f32 v[2:3], v[2:3], v[4:5]
	s_nop 0
	v_cvt_pk_bf16_f32 v1, v2, v3
	global_store_dwordx2 v[16:17], v[0:1], off offset:112
	v_add_u32_e32 v0, s14, v119
	s_add_u32 s0, s90, s0
	s_addc_u32 s1, s91, s1
	v_lshl_or_b32 v31, v0, 10, v176
	v_lshl_add_u64 v[0:1], s[0:1], 0, v[182:183]
	v_ashrrev_i32_e32 v12, 5, v31
	v_lshl_add_u64 v[18:19], v[0:1], 0, s[2:3]
	v_lshl_add_u64 v[0:1], s[0:1], 0, v[184:185]
	v_ashrrev_i32_e32 v13, 31, v12
	v_lshl_add_u64 v[16:17], v[0:1], 0, s[94:95]
	v_lshl_add_u64 v[0:1], v[12:13], 4, v[18:19]
	v_lshl_add_u64 v[4:5], v[12:13], 0, s[96:97]
	global_load_dword v2, v[0:1], off
	v_lshl_add_u64 v[0:1], v[4:5], 4, v[18:19]
	v_lshl_add_u64 v[6:7], v[12:13], 0, s[4:5]
	global_load_dword v3, v[0:1], off
	v_lshl_add_u64 v[0:1], v[6:7], 4, v[18:19]
	global_load_dword v0, v[0:1], off
	v_mov_b64_e32 v[20:21], s[0:1]
	v_lshlrev_b64 v[4:5], 9, v[4:5]
	v_mad_i64_i32 v[22:23], s[0:1], v12, s33, v[20:21]
	v_lshl_add_u64 v[4:5], v[16:17], 0, v[4:5]
	v_lshl_add_u64 v[26:27], v[22:23], 0, v[184:185]
	s_add_i32 s6, s6, 1
	v_mov_b32_e32 v168, s93
	v_mov_b32_e32 v169, 0
	v_mov_b32_e32 v161, 0
	v_add_u32_e32 v160, 0x100, v31
	v_ashrrev_i32_e32 v160, 5, v160
	v_lshl_add_u64 v[162:163], v[160:161], 0, s[96:97]
	v_lshl_add_u64 v[164:165], v[160:161], 0, s[4:5]
	v_lshl_add_u64 v[166:167], v[160:161], 4, v[18:19]
	global_load_dword v150, v[166:167], off
	v_lshl_add_u64 v[166:167], v[162:163], 4, v[18:19]
	global_load_dword v151, v[166:167], off
	v_lshl_add_u64 v[166:167], v[164:165], 4, v[18:19]
	global_load_dword v152, v[166:167], off
	v_lshl_add_u64 v[162:163], v[160:161], 0, s[96:97]
	v_lshl_add_u64 v[164:165], v[160:161], 0, s[4:5]
	v_lshlrev_b64 v[166:167], 9, v[160:161]
	v_lshl_add_u64 v[166:167], v[16:17], 0, v[166:167]
	global_load_dwordx4 v[56:59], v[166:167], off
	v_lshlrev_b64 v[166:167], 9, v[162:163]
	v_lshl_add_u64 v[166:167], v[16:17], 0, v[166:167]
	global_load_dwordx4 v[60:63], v[166:167], off
	v_lshlrev_b64 v[166:167], 9, v[164:165]
	v_lshl_add_u64 v[166:167], v[16:17], 0, v[166:167]
	global_load_dwordx4 v[100:103], v[166:167], off
	v_mad_i64_i32 v[166:167], s[0:1], v160, s33, v[20:21]
	v_lshl_add_u64 v[166:167], v[166:167], 0, v[184:185]
	v_lshl_add_u64 v[166:167], v[166:167], 0, v[168:169]
	global_load_dwordx4 v[104:107], v[166:167], off offset:3328
	v_add_u32_e32 v160, 0x200, v31
	v_ashrrev_i32_e32 v160, 5, v160
	v_lshl_add_u64 v[162:163], v[160:161], 0, s[96:97]
	v_lshl_add_u64 v[164:165], v[160:161], 0, s[4:5]
	v_lshl_add_u64 v[166:167], v[160:161], 4, v[18:19]
	global_load_dword v153, v[166:167], off
	v_lshl_add_u64 v[166:167], v[162:163], 4, v[18:19]
	global_load_dword v154, v[166:167], off
	v_lshl_add_u64 v[166:167], v[164:165], 4, v[18:19]
	global_load_dword v155, v[166:167], off
	v_lshl_add_u64 v[162:163], v[160:161], 0, s[96:97]
	v_lshl_add_u64 v[164:165], v[160:161], 0, s[4:5]
	v_lshlrev_b64 v[166:167], 9, v[160:161]
	v_lshl_add_u64 v[166:167], v[16:17], 0, v[166:167]
	global_load_dwordx4 v[108:111], v[166:167], off
	v_lshlrev_b64 v[166:167], 9, v[162:163]
	v_lshl_add_u64 v[166:167], v[16:17], 0, v[166:167]
	global_load_dwordx4 v[112:115], v[166:167], off
	v_lshlrev_b64 v[166:167], 9, v[164:165]
	v_lshl_add_u64 v[166:167], v[16:17], 0, v[166:167]
	global_load_dwordx4 v[120:123], v[166:167], off
	v_mad_i64_i32 v[166:167], s[0:1], v160, s33, v[20:21]
	v_lshl_add_u64 v[166:167], v[166:167], 0, v[184:185]
	v_lshl_add_u64 v[166:167], v[166:167], 0, v[168:169]
	global_load_dwordx4 v[124:127], v[166:167], off offset:3328
	v_add_u32_e32 v160, 0x300, v31
	v_ashrrev_i32_e32 v160, 5, v160
	v_lshl_add_u64 v[162:163], v[160:161], 0, s[96:97]
	v_lshl_add_u64 v[164:165], v[160:161], 0, s[4:5]
	v_lshl_add_u64 v[166:167], v[160:161], 4, v[18:19]
	global_load_dword v156, v[166:167], off
	v_lshl_add_u64 v[166:167], v[162:163], 4, v[18:19]
	global_load_dword v157, v[166:167], off
	v_lshl_add_u64 v[166:167], v[164:165], 4, v[18:19]
	global_load_dword v158, v[166:167], off
	v_lshl_add_u64 v[162:163], v[160:161], 0, s[96:97]
	v_lshl_add_u64 v[164:165], v[160:161], 0, s[4:5]
	v_lshlrev_b64 v[166:167], 9, v[160:161]
	v_lshl_add_u64 v[166:167], v[16:17], 0, v[166:167]
	global_load_dwordx4 v[128:131], v[166:167], off
	v_lshlrev_b64 v[166:167], 9, v[162:163]
	v_lshl_add_u64 v[166:167], v[16:17], 0, v[166:167]
	global_load_dwordx4 v[132:135], v[166:167], off
	v_lshlrev_b64 v[166:167], 9, v[164:165]
	v_lshl_add_u64 v[166:167], v[16:17], 0, v[166:167]
	global_load_dwordx4 v[136:139], v[166:167], off
	v_mad_i64_i32 v[166:167], s[0:1], v160, s33, v[20:21]
	v_lshl_add_u64 v[166:167], v[166:167], 0, v[184:185]
	v_lshl_add_u64 v[166:167], v[166:167], 0, v[168:169]
	global_load_dwordx4 v[140:143], v[166:167], off offset:3328
	v_lshl_add_u64 v[162:163], v[12:13], 0, s[96:97]
	v_lshl_add_u64 v[164:165], v[12:13], 0, s[4:5]
	v_lshlrev_b64 v[166:167], 9, v[12:13]
	v_lshl_add_u64 v[166:167], v[16:17], 0, v[166:167]
	global_load_dwordx4 v[40:43], v[166:167], off
	v_lshlrev_b64 v[166:167], 9, v[162:163]
	v_lshl_add_u64 v[166:167], v[16:17], 0, v[166:167]
	global_load_dwordx4 v[44:47], v[166:167], off
	v_lshlrev_b64 v[166:167], 9, v[164:165]
	v_lshl_add_u64 v[166:167], v[16:17], 0, v[166:167]
	global_load_dwordx4 v[48:51], v[166:167], off
	v_mad_i64_i32 v[166:167], s[0:1], v12, s33, v[20:21]
	v_lshl_add_u64 v[166:167], v[166:167], 0, v[184:185]
	v_lshl_add_u64 v[166:167], v[166:167], 0, v[168:169]
	global_load_dwordx4 v[52:55], v[166:167], off offset:3328
	s_waitcnt vmcnt(0)
; DI float lo16(unsigned w) { return __uint_as_float(w << 16); }
; DI float hi16(unsigned w) { return __uint_as_float(w & 0xffff0000u); }
; DI float siluf_(float x) { return x / (1.f + __expf(-x)); }
; DI void dilcomb_item(const Params& p, int it) {
;     ...
;     const float l0 = lse[((size_t)0 * T_ + tok) * 4 + h], l1 = lse[((size_t)1 * T_ + tok) * 4 + h], l2 = lse[((size_t)2 * T_ + tok) * 4 + h];
;     const float mx = fmaxf(l0, fmaxf(l1, l2));
;     float w0 = __expf(l0 - mx), w1 = __expf(l1 - mx), w2 = __expf(l2 - mx);
;     const float iw = 1.f / (w0 + w1 + w2); w0 *= iw; w1 *= iw; w2 *= iw;
;     const u32x4 a = *(const u32x4*)(od + ((size_t)0 * T_ + tok) * 256 + c8 * 8), bq = *(const u32x4*)(od + ((size_t)1 * T_ + tok) * 256 + c8 * 8), cq = *(const u32x4*)(od + ((size_t)2 * T_ + tok) * 256 + c8 * 8);
;     const u32x4 z = *(const u32x4*)(proj + tok * NP + C_BZ + c8 * 8);
;     u32x4 r;
; #pragma unroll
;     for (int e = 0; e < 4; ++e) {
;       const float v0 = (w0 * lo16(a[e]) + w1 * lo16(bq[e]) + w2 * lo16(cq[e])) * siluf_(lo16(z[e]));
;       const float v1 = (w0 * hi16(a[e]) + w1 * hi16(bq[e]) + w2 * hi16(cq[e])) * siluf_(hi16(z[e]));
;       r[e] = pk2(v0, v1);
;     }
;     *(u32x4*)(y + tok * 1024 + 256 + c8 * 8) = r;
	v_max3_f32 v1, v2, v3, v0
	v_sub_f32_e32 v2, v2, v1
	v_mul_f32_e32 v2, 0x3fb8aa3b, v2
	v_exp_f32_e32 v25, v2
	v_sub_f32_e32 v2, v3, v1
	v_mul_f32_e32 v2, 0x3fb8aa3b, v2
	v_sub_f32_e32 v0, v0, v1
	v_exp_f32_e32 v24, v2
	v_mul_f32_e32 v0, 0x3fb8aa3b, v0
	v_exp_f32_e32 v0, v0
	v_add_f32_e32 v1, v25, v24
	v_add_f32_e32 v1, v0, v1
	s_nop 0
	v_rcp_f32_e32 v30, v1
	s_nop 0
	v_mul_f32_e32 v14, v0, v30
	v_lshlrev_b64 v[0:1], 9, v[12:13]
	v_lshl_add_u64 v[0:1], v[16:17], 0, v[0:1]
	v_mov_b32_e32 v0, v40
	v_mov_b32_e32 v1, v41
	v_mov_b32_e32 v2, v42
	v_mov_b32_e32 v3, v43
	v_add_co_u32_e32 v26, vcc, s93, v26
	v_mov_b32_e32 v8, v44
	v_mov_b32_e32 v9, v45
	v_mov_b32_e32 v10, v46
	v_mov_b32_e32 v11, v47
	v_lshlrev_b64 v[4:5], 9, v[6:7]
	v_lshl_add_u64 v[4:5], v[16:17], 0, v[4:5]
	v_addc_co_u32_e32 v27, vcc, 0, v27, vcc
	v_mov_b32_e32 v4, v48
	v_mov_b32_e32 v5, v49
	v_mov_b32_e32 v6, v50
	v_mov_b32_e32 v7, v51
	v_pk_mul_f32 v[24:25], v[24:25], v[30:31] op_sel_hi:[1,0]
	v_mov_b32_e32 v26, v52
	v_mov_b32_e32 v27, v53
	v_mov_b32_e32 v28, v54
	v_mov_b32_e32 v29, v55
	v_and_b32_e32 v35, 0xffff0000, v0
	v_lshlrev_b32_e32 v36, 16, v0
	v_lshlrev_b32_e32 v34, 16, v8
	v_and_b32_e32 v37, 0xffff0000, v8
	v_pk_mul_f32 v[36:37], v[24:25], v[36:37] op_sel:[1,0] op_sel_hi:[0,1]
	v_pk_fma_f32 v[34:35], v[24:25], v[34:35], v[36:37]
	v_lshlrev_b32_e32 v38, 16, v4
	v_and_b32_e32 v39, 0xffff0000, v4
	v_lshlrev_b32_e32 v13, 16, v26
	v_and_b32_e32 v15, 0xffff0000, v26
	v_mul_f32_e32 v26, 0xbfb8aa3b, v13
	v_mul_f32_e32 v0, 0xbfb8aa3b, v15
	v_exp_f32_e32 v32, v26
	v_exp_f32_e32 v33, v0
	s_nop 0
	v_pk_add_f32 v[32:33], v[32:33], 1.0 op_sel_hi:[1,0]
	s_nop 0
	s_nop 0
	v_rcp_f32_e32 v33, v33
	s_nop 0
	v_mul_f32_e32 v33, v15, v33
	v_div_scale_f32 v0, s[0:1], v32, v32, v13
	v_rcp_f32_e32 v4, v0
	s_nop 0
	v_fma_f32 v8, -v0, v4, 1.0
	v_fmac_f32_e32 v4, v8, v4
	v_div_scale_f32 v8, vcc, v13, v32, v13
	v_mul_f32_e32 v15, v8, v4
	v_fma_f32 v26, -v0, v15, v8
	v_fmac_f32_e32 v15, v26, v4
	v_fma_f32 v0, -v0, v15, v8
	v_div_fmas_f32 v0, v0, v4, v15
	v_div_fixup_f32 v32, v0, v32, v13
	v_pk_fma_f32 v[34:35], v[14:15], v[38:39], v[34:35] op_sel_hi:[0,1,1]
	v_lshlrev_b32_e32 v13, 16, v27
	v_and_b32_e32 v15, 0xffff0000, v27
	v_pk_mul_f32 v[32:33], v[32:33], v[34:35]
	v_mul_f32_e32 v4, 0xbfb8aa3b, v13
	v_and_b32_e32 v27, 0xffff0000, v1
	v_lshlrev_b32_e32 v8, 16, v1
	v_mul_f32_e32 v1, 0xbfb8aa3b, v15
	v_cvt_pk_bf16_f32 v0, v32, v33
	v_exp_f32_e32 v4, v4
	v_lshlrev_b32_e32 v32, 16, v5
	v_and_b32_e32 v33, 0xffff0000, v5
	v_exp_f32_e32 v5, v1
	v_lshlrev_b32_e32 v26, 16, v9
	v_and_b32_e32 v9, 0xffff0000, v9
	v_pk_mul_f32 v[8:9], v[24:25], v[8:9] op_sel:[1,0] op_sel_hi:[0,1]
	v_pk_add_f32 v[4:5], v[4:5], 1.0 op_sel_hi:[1,0]
	v_pk_fma_f32 v[8:9], v[24:25], v[26:27], v[8:9]
	v_lshlrev_b32_e32 v26, 16, v2
	v_and_b32_e32 v27, 0xffff0000, v10
	v_pk_mul_f32 v[26:27], v[24:25], v[26:27] op_sel:[1,0] op_sel_hi:[0,1]
	v_rcp_f32_e32 v5, v5
	s_nop 0
	v_mul_f32_e32 v5, v15, v5
	v_div_scale_f32 v1, s[0:1], v4, v4, v13
	v_rcp_f32_e32 v15, v1
	s_nop 0
	v_fma_f32 v30, -v1, v15, 1.0
	v_fmac_f32_e32 v15, v30, v15
	v_div_scale_f32 v30, vcc, v13, v4, v13
	v_mul_f32_e32 v34, v30, v15
	v_fma_f32 v35, -v1, v34, v30
	v_fmac_f32_e32 v34, v35, v15
	v_fma_f32 v1, -v1, v34, v30
	v_div_fmas_f32 v1, v1, v15, v34
	v_div_fixup_f32 v4, v1, v4, v13
	v_pk_fma_f32 v[8:9], v[14:15], v[32:33], v[8:9] op_sel_hi:[0,1,1]
	v_pk_mul_f32 v[4:5], v[4:5], v[8:9]
	v_lshlrev_b32_e32 v13, 16, v28
	v_and_b32_e32 v15, 0xffff0000, v28
	v_cvt_pk_bf16_f32 v1, v4, v5
	v_mul_f32_e32 v4, 0xbfb8aa3b, v13
	v_and_b32_e32 v9, 0xffff0000, v2
	v_mul_f32_e32 v2, 0xbfb8aa3b, v15
	v_exp_f32_e32 v4, v4
	v_exp_f32_e32 v5, v2
	v_lshlrev_b32_e32 v32, 16, v6
	v_and_b32_e32 v33, 0xffff0000, v6
	v_lshlrev_b32_e32 v8, 16, v10
	v_pk_add_f32 v[4:5], v[4:5], 1.0 op_sel_hi:[1,0]
	v_pk_fma_f32 v[8:9], v[24:25], v[8:9], v[26:27]
	s_nop 0
	v_rcp_f32_e32 v5, v5
	s_nop 0
	v_mul_f32_e32 v5, v15, v5
	v_div_scale_f32 v2, s[0:1], v4, v4, v13
	v_rcp_f32_e32 v6, v2
	s_nop 0
	v_fma_f32 v10, -v2, v6, 1.0
	v_fmac_f32_e32 v6, v10, v6
	v_div_scale_f32 v10, vcc, v13, v4, v13
	v_mul_f32_e32 v15, v10, v6
	v_fma_f32 v28, -v2, v15, v10
	v_fmac_f32_e32 v15, v28, v6
	v_fma_f32 v2, -v2, v15, v10
	v_div_fmas_f32 v2, v2, v6, v15
	v_div_fixup_f32 v4, v2, v4, v13
	v_pk_fma_f32 v[8:9], v[14:15], v[32:33], v[8:9] op_sel_hi:[0,1,1]
	v_pk_mul_f32 v[4:5], v[4:5], v[8:9]
	v_lshlrev_b32_e32 v13, 16, v29
	v_and_b32_e32 v15, 0xffff0000, v29
	v_cvt_pk_bf16_f32 v2, v4, v5
	v_mul_f32_e32 v4, 0xbfb8aa3b, v13
	v_and_b32_e32 v9, 0xffff0000, v3
	v_lshlrev_b32_e32 v10, 16, v3
	v_mul_f32_e32 v3, 0xbfb8aa3b, v15
	v_exp_f32_e32 v4, v4
	v_exp_f32_e32 v5, v3
	v_lshlrev_b32_e32 v8, 16, v11
	v_and_b32_e32 v11, 0xffff0000, v11
	v_pk_mul_f32 v[10:11], v[24:25], v[10:11] op_sel:[1,0] op_sel_hi:[0,1]
	v_pk_add_f32 v[4:5], v[4:5], 1.0 op_sel_hi:[1,0]
	v_pk_fma_f32 v[8:9], v[24:25], v[8:9], v[10:11]
	v_lshlrev_b32_e32 v6, 16, v7
	v_and_b32_e32 v7, 0xffff0000, v7
	v_pk_fma_f32 v[6:7], v[14:15], v[6:7], v[8:9] op_sel_hi:[0,1,1]
	s_nop 0
	v_rcp_f32_e32 v5, v5
	s_nop 0
	v_mul_f32_e32 v5, v15, v5
	s_nop 0
	v_rcp_f32_e32 v4, v4
	s_nop 0
	v_mul_f32_e32 v4, v13, v4
	v_pk_mul_f32 v[4:5], v[4:5], v[6:7]
	s_nop 0
	v_cvt_pk_bf16_f32 v3, v4, v5
	v_mad_i64_i32 v[4:5], s[0:1], v12, s37, v[22:23]
	v_lshl_add_u64 v[4:5], v[4:5], 0, v[184:185]
	v_add_co_u32_e32 v4, vcc, s74, v4
	s_nop 1
	v_addc_co_u32_e32 v5, vcc, 0, v5, vcc
	global_store_dwordx4 v[4:5], v[0:3], off offset:512
	s_nop 1
	v_add_u32_e32 v0, 0x100, v31
	v_ashrrev_i32_e32 v22, 5, v0
	v_ashrrev_i32_e32 v23, 31, v22
	v_lshl_add_u64 v[0:1], v[22:23], 4, v[18:19]
	v_lshl_add_u64 v[4:5], v[22:23], 0, s[96:97]
; DI float lo16(unsigned w) { return __uint_as_float(w << 16); }
; DI float hi16(unsigned w) { return __uint_as_float(w & 0xffff0000u); }
; DI float siluf_(float x) { return x / (1.f + __expf(-x)); }
; DI void dilcomb_item(const Params& p, int it) {
;     ...
;     const float l0 = lse[((size_t)0 * T_ + tok) * 4 + h], l1 = lse[((size_t)1 * T_ + tok) * 4 + h], l2 = lse[((size_t)2 * T_ + tok) * 4 + h];
;     const float mx = fmaxf(l0, fmaxf(l1, l2));
;     float w0 = __expf(l0 - mx), w1 = __expf(l1 - mx), w2 = __expf(l2 - mx);
;     const float iw = 1.f / (w0 + w1 + w2); w0 *= iw; w1 *= iw; w2 *= iw;
;     const u32x4 a = *(const u32x4*)(od + ((size_t)0 * T_ + tok) * 256 + c8 * 8), bq = *(const u32x4*)(od + ((size_t)1 * T_ + tok) * 256 + c8 * 8), cq = *(const u32x4*)(od + ((size_t)2 * T_ + tok) * 256 + c8 * 8);
;     const u32x4 z = *(const u32x4*)(proj + tok * NP + C_BZ + c8 * 8);
;     u32x4 r;
; #pragma unroll
;     for (int e = 0; e < 4; ++e) {
;       const float v0 = (w0 * lo16(a[e]) + w1 * lo16(bq[e]) + w2 * lo16(cq[e])) * siluf_(lo16(z[e]));
;       const float v1 = (w0 * hi16(a[e]) + w1 * hi16(bq[e]) + w2 * hi16(cq[e])) * siluf_(hi16(z[e]));
;       r[e] = pk2(v0, v1);
;     }
;     *(u32x4*)(y + tok * 1024 + 256 + c8 * 8) = r;
	v_mov_b32_e32 v2, v150
	v_lshl_add_u64 v[0:1], v[4:5], 4, v[18:19]
	v_lshl_add_u64 v[6:7], v[22:23], 0, s[4:5]
	v_mov_b32_e32 v3, v151
	v_lshl_add_u64 v[0:1], v[6:7], 4, v[18:19]
	v_mov_b32_e32 v0, v152
	v_lshlrev_b64 v[4:5], 9, v[4:5]
	v_mad_i64_i32 v[26:27], s[0:1], v22, s33, v[20:21]
	v_lshl_add_u64 v[4:5], v[16:17], 0, v[4:5]
	v_lshl_add_u64 v[12:13], v[26:27], 0, v[184:185]
	v_max3_f32 v1, v2, v3, v0
	v_sub_f32_e32 v2, v2, v1
	v_mul_f32_e32 v2, 0x3fb8aa3b, v2
	v_exp_f32_e32 v29, v2
	v_sub_f32_e32 v2, v3, v1
	v_mul_f32_e32 v2, 0x3fb8aa3b, v2
	v_sub_f32_e32 v0, v0, v1
	v_exp_f32_e32 v28, v2
	v_mul_f32_e32 v0, 0x3fb8aa3b, v0
	v_exp_f32_e32 v0, v0
	v_add_f32_e32 v1, v29, v28
	v_add_f32_e32 v1, v0, v1
	s_nop 0
	v_rcp_f32_e32 v30, v1
	s_nop 0
	v_mul_f32_e32 v24, v0, v30
	v_lshlrev_b64 v[0:1], 9, v[22:23]
	v_lshl_add_u64 v[0:1], v[16:17], 0, v[0:1]
	v_mov_b32_e32 v0, v56
	v_mov_b32_e32 v1, v57
	v_mov_b32_e32 v2, v58
	v_mov_b32_e32 v3, v59
	v_add_co_u32_e32 v12, vcc, s93, v12
	v_mov_b32_e32 v8, v60
	v_mov_b32_e32 v9, v61
	v_mov_b32_e32 v10, v62
	v_mov_b32_e32 v11, v63
	v_lshlrev_b64 v[4:5], 9, v[6:7]
	v_lshl_add_u64 v[4:5], v[16:17], 0, v[4:5]
	v_addc_co_u32_e32 v13, vcc, 0, v13, vcc
	v_mov_b32_e32 v4, v100
	v_mov_b32_e32 v5, v101
	v_mov_b32_e32 v6, v102
	v_mov_b32_e32 v7, v103
	v_pk_mul_f32 v[28:29], v[28:29], v[30:31] op_sel_hi:[1,0]
	v_mov_b32_e32 v12, v104
	v_mov_b32_e32 v13, v105
	v_mov_b32_e32 v14, v106
	v_mov_b32_e32 v15, v107
	v_and_b32_e32 v35, 0xffff0000, v0
	v_lshlrev_b32_e32 v36, 16, v0
	v_lshlrev_b32_e32 v34, 16, v8
	v_and_b32_e32 v37, 0xffff0000, v8
	v_pk_mul_f32 v[36:37], v[28:29], v[36:37] op_sel:[1,0] op_sel_hi:[0,1]
	v_pk_fma_f32 v[34:35], v[28:29], v[34:35], v[36:37]
	v_lshlrev_b32_e32 v38, 16, v4
	v_and_b32_e32 v39, 0xffff0000, v4
	v_lshlrev_b32_e32 v23, 16, v12
	v_and_b32_e32 v12, 0xffff0000, v12
	v_mul_f32_e32 v25, 0xbfb8aa3b, v23
	v_mul_f32_e32 v0, 0xbfb8aa3b, v12
	v_exp_f32_e32 v32, v25
	v_exp_f32_e32 v33, v0
	s_nop 0
	v_pk_add_f32 v[32:33], v[32:33], 1.0 op_sel_hi:[1,0]
	s_nop 0
	s_nop 0
	v_rcp_f32_e32 v33, v33
	s_nop 0
	v_mul_f32_e32 v33, v12, v33
	v_div_scale_f32 v0, s[0:1], v32, v32, v23
	v_rcp_f32_e32 v4, v0
	s_nop 0
	v_fma_f32 v8, -v0, v4, 1.0
	v_fmac_f32_e32 v4, v8, v4
	v_div_scale_f32 v8, vcc, v23, v32, v23
	v_mul_f32_e32 v12, v8, v4
	v_fma_f32 v25, -v0, v12, v8
	v_fmac_f32_e32 v12, v25, v4
	v_fma_f32 v0, -v0, v12, v8
	v_div_fmas_f32 v0, v0, v4, v12
	v_div_fixup_f32 v32, v0, v32, v23
	v_pk_fma_f32 v[34:35], v[24:25], v[38:39], v[34:35] op_sel_hi:[0,1,1]
	v_lshlrev_b32_e32 v23, 16, v13
	v_and_b32_e32 v25, 0xffff0000, v13
	v_pk_mul_f32 v[32:33], v[32:33], v[34:35]
	v_mul_f32_e32 v4, 0xbfb8aa3b, v23
	v_and_b32_e32 v13, 0xffff0000, v1
	v_lshlrev_b32_e32 v8, 16, v1
	v_mul_f32_e32 v1, 0xbfb8aa3b, v25
	v_cvt_pk_bf16_f32 v0, v32, v33
	v_exp_f32_e32 v4, v4
	v_lshlrev_b32_e32 v32, 16, v5
	v_and_b32_e32 v33, 0xffff0000, v5
	v_exp_f32_e32 v5, v1
	v_lshlrev_b32_e32 v12, 16, v9
	v_and_b32_e32 v9, 0xffff0000, v9
	v_pk_mul_f32 v[8:9], v[28:29], v[8:9] op_sel:[1,0] op_sel_hi:[0,1]
	v_pk_add_f32 v[4:5], v[4:5], 1.0 op_sel_hi:[1,0]
	v_pk_fma_f32 v[8:9], v[28:29], v[12:13], v[8:9]
	v_lshlrev_b32_e32 v12, 16, v2
	v_and_b32_e32 v13, 0xffff0000, v10
	v_pk_mul_f32 v[12:13], v[28:29], v[12:13] op_sel:[1,0] op_sel_hi:[0,1]
	v_rcp_f32_e32 v5, v5
	s_nop 0
	v_mul_f32_e32 v5, v25, v5
	v_div_scale_f32 v1, s[0:1], v4, v4, v23
	v_rcp_f32_e32 v25, v1
	s_nop 0
	v_fma_f32 v30, -v1, v25, 1.0
	v_fmac_f32_e32 v25, v30, v25
	v_div_scale_f32 v30, vcc, v23, v4, v23
	v_mul_f32_e32 v34, v30, v25
	v_fma_f32 v35, -v1, v34, v30
	v_fmac_f32_e32 v34, v35, v25
	v_fma_f32 v1, -v1, v34, v30
	v_div_fmas_f32 v1, v1, v25, v34
	v_div_fixup_f32 v4, v1, v4, v23
	v_pk_fma_f32 v[8:9], v[24:25], v[32:33], v[8:9] op_sel_hi:[0,1,1]
	v_pk_mul_f32 v[4:5], v[4:5], v[8:9]
	v_lshlrev_b32_e32 v23, 16, v14
	v_and_b32_e32 v14, 0xffff0000, v14
	v_cvt_pk_bf16_f32 v1, v4, v5
	v_mul_f32_e32 v4, 0xbfb8aa3b, v23
	v_and_b32_e32 v9, 0xffff0000, v2
	v_mul_f32_e32 v2, 0xbfb8aa3b, v14
	v_exp_f32_e32 v4, v4
	v_exp_f32_e32 v5, v2
	v_lshlrev_b32_e32 v32, 16, v6
	v_and_b32_e32 v33, 0xffff0000, v6
	v_lshlrev_b32_e32 v8, 16, v10
	v_pk_add_f32 v[4:5], v[4:5], 1.0 op_sel_hi:[1,0]
	v_pk_fma_f32 v[8:9], v[28:29], v[8:9], v[12:13]
	v_lshlrev_b32_e32 v12, 16, v15
	v_and_b32_e32 v13, 0xffff0000, v15
	v_rcp_f32_e32 v5, v5
	s_nop 0
	v_mul_f32_e32 v5, v14, v5
	v_div_scale_f32 v2, s[0:1], v4, v4, v23
	v_rcp_f32_e32 v6, v2
	s_nop 0
	v_fma_f32 v10, -v2, v6, 1.0
	v_fmac_f32_e32 v6, v10, v6
	v_div_scale_f32 v10, vcc, v23, v4, v23
	v_mul_f32_e32 v14, v10, v6
	v_fma_f32 v25, -v2, v14, v10
	v_fmac_f32_e32 v14, v25, v6
	v_fma_f32 v2, -v2, v14, v10
	v_div_fmas_f32 v2, v2, v6, v14
	v_div_fixup_f32 v4, v2, v4, v23
	v_pk_fma_f32 v[8:9], v[24:25], v[32:33], v[8:9] op_sel_hi:[0,1,1]
	v_pk_mul_f32 v[4:5], v[4:5], v[8:9]
	v_and_b32_e32 v9, 0xffff0000, v3
	v_cvt_pk_bf16_f32 v2, v4, v5
	v_mul_f32_e32 v4, 0xbfb8aa3b, v12
	v_lshlrev_b32_e32 v10, 16, v3
	v_mul_f32_e32 v3, 0xbfb8aa3b, v13
	v_exp_f32_e32 v4, v4
	v_exp_f32_e32 v5, v3
	v_lshlrev_b32_e32 v8, 16, v11
	v_and_b32_e32 v11, 0xffff0000, v11
	v_pk_mul_f32 v[10:11], v[28:29], v[10:11] op_sel:[1,0] op_sel_hi:[0,1]
	v_pk_add_f32 v[4:5], v[4:5], 1.0 op_sel_hi:[1,0]
	v_pk_fma_f32 v[8:9], v[28:29], v[8:9], v[10:11]
	v_lshlrev_b32_e32 v6, 16, v7
	v_and_b32_e32 v7, 0xffff0000, v7
	v_pk_fma_f32 v[6:7], v[24:25], v[6:7], v[8:9] op_sel_hi:[0,1,1]
	s_nop 0
	v_rcp_f32_e32 v5, v5
	s_nop 0
	v_mul_f32_e32 v5, v13, v5
	s_nop 0
	v_rcp_f32_e32 v4, v4
	s_nop 0
	v_mul_f32_e32 v4, v12, v4
	v_pk_mul_f32 v[4:5], v[4:5], v[6:7]
	s_nop 0
	v_cvt_pk_bf16_f32 v3, v4, v5
	v_mad_i64_i32 v[4:5], s[0:1], v22, s37, v[26:27]
; DI float lo16(unsigned w) { return __uint_as_float(w << 16); }
; DI float hi16(unsigned w) { return __uint_as_float(w & 0xffff0000u); }
; DI float siluf_(float x) { return x / (1.f + __expf(-x)); }
; DI void dilcomb_item(const Params& p, int it) {
;     ...
;     const float l0 = lse[((size_t)0 * T_ + tok) * 4 + h], l1 = lse[((size_t)1 * T_ + tok) * 4 + h], l2 = lse[((size_t)2 * T_ + tok) * 4 + h];
;     const float mx = fmaxf(l0, fmaxf(l1, l2));
;     float w0 = __expf(l0 - mx), w1 = __expf(l1 - mx), w2 = __expf(l2 - mx);
;     const float iw = 1.f / (w0 + w1 + w2); w0 *= iw; w1 *= iw; w2 *= iw;
;     const u32x4 a = *(const u32x4*)(od + ((size_t)0 * T_ + tok) * 256 + c8 * 8), bq = *(const u32x4*)(od + ((size_t)1 * T_ + tok) * 256 + c8 * 8), cq = *(const u32x4*)(od + ((size_t)2 * T_ + tok) * 256 + c8 * 8);
;     const u32x4 z = *(const u32x4*)(proj + tok * NP + C_BZ + c8 * 8);
;     u32x4 r;
; #pragma unroll
;     for (int e = 0; e < 4; ++e) {
;       const float v0 = (w0 * lo16(a[e]) + w1 * lo16(bq[e]) + w2 * lo16(cq[e])) * siluf_(lo16(z[e]));
;       const float v1 = (w0 * hi16(a[e]) + w1 * hi16(bq[e]) + w2 * hi16(cq[e])) * siluf_(hi16(z[e]));
;       r[e] = pk2(v0, v1);
;     }
;     *(u32x4*)(y + tok * 1024 + 256 + c8 * 8) = r;
	v_lshl_add_u64 v[4:5], v[4:5], 0, v[184:185]
	v_add_co_u32_e32 v4, vcc, s74, v4
	s_nop 1
	v_addc_co_u32_e32 v5, vcc, 0, v5, vcc
	global_store_dwordx4 v[4:5], v[0:3], off offset:512
	s_nop 1
	v_add_u32_e32 v0, 0x200, v31
	v_ashrrev_i32_e32 v12, 5, v0
	v_ashrrev_i32_e32 v13, 31, v12
	v_lshl_add_u64 v[0:1], v[12:13], 4, v[18:19]
	v_lshl_add_u64 v[4:5], v[12:13], 0, s[96:97]
	v_mov_b32_e32 v2, v153
	v_lshl_add_u64 v[0:1], v[4:5], 4, v[18:19]
	v_lshl_add_u64 v[6:7], v[12:13], 0, s[4:5]
	v_mov_b32_e32 v3, v154
	v_lshl_add_u64 v[0:1], v[6:7], 4, v[18:19]
	v_mov_b32_e32 v0, v155
	v_lshlrev_b64 v[4:5], 9, v[4:5]
	v_mad_i64_i32 v[22:23], s[0:1], v12, s33, v[20:21]
	v_lshl_add_u64 v[4:5], v[16:17], 0, v[4:5]
	v_lshl_add_u64 v[24:25], v[22:23], 0, v[184:185]
	v_max3_f32 v1, v2, v3, v0
	v_sub_f32_e32 v2, v2, v1
	v_mul_f32_e32 v2, 0x3fb8aa3b, v2
	v_exp_f32_e32 v29, v2
	v_sub_f32_e32 v2, v3, v1
	v_mul_f32_e32 v2, 0x3fb8aa3b, v2
	v_sub_f32_e32 v0, v0, v1
	v_exp_f32_e32 v28, v2
	v_mul_f32_e32 v0, 0x3fb8aa3b, v0
	v_exp_f32_e32 v0, v0
	v_add_f32_e32 v1, v29, v28
	v_add_f32_e32 v1, v0, v1
	s_nop 0
	v_rcp_f32_e32 v30, v1
	s_nop 0
	v_mul_f32_e32 v14, v0, v30
	v_lshlrev_b64 v[0:1], 9, v[12:13]
	v_lshl_add_u64 v[0:1], v[16:17], 0, v[0:1]
	v_mov_b32_e32 v0, v108
	v_mov_b32_e32 v1, v109
	v_mov_b32_e32 v2, v110
	v_mov_b32_e32 v3, v111
	v_add_co_u32_e32 v24, vcc, s93, v24
	v_mov_b32_e32 v8, v112
	v_mov_b32_e32 v9, v113
	v_mov_b32_e32 v10, v114
	v_mov_b32_e32 v11, v115
	v_lshlrev_b64 v[4:5], 9, v[6:7]
	v_lshl_add_u64 v[4:5], v[16:17], 0, v[4:5]
	v_addc_co_u32_e32 v25, vcc, 0, v25, vcc
	v_mov_b32_e32 v4, v120
	v_mov_b32_e32 v5, v121
	v_mov_b32_e32 v6, v122
	v_mov_b32_e32 v7, v123
	v_pk_mul_f32 v[28:29], v[28:29], v[30:31] op_sel_hi:[1,0]
	v_mov_b32_e32 v24, v124
	v_mov_b32_e32 v25, v125
	v_mov_b32_e32 v26, v126
	v_mov_b32_e32 v27, v127
	v_and_b32_e32 v35, 0xffff0000, v0
	v_lshlrev_b32_e32 v36, 16, v0
	v_lshlrev_b32_e32 v34, 16, v8
	v_and_b32_e32 v37, 0xffff0000, v8
	v_pk_mul_f32 v[36:37], v[28:29], v[36:37] op_sel:[1,0] op_sel_hi:[0,1]
	v_pk_fma_f32 v[34:35], v[28:29], v[34:35], v[36:37]
	v_lshlrev_b32_e32 v38, 16, v4
	v_and_b32_e32 v39, 0xffff0000, v4
	v_lshlrev_b32_e32 v13, 16, v24
	v_and_b32_e32 v15, 0xffff0000, v24
	v_mul_f32_e32 v24, 0xbfb8aa3b, v13
	v_mul_f32_e32 v0, 0xbfb8aa3b, v15
	v_exp_f32_e32 v32, v24
	v_exp_f32_e32 v33, v0
	s_nop 0
	v_pk_add_f32 v[32:33], v[32:33], 1.0 op_sel_hi:[1,0]
	s_nop 0
	s_nop 0
	v_rcp_f32_e32 v33, v33
	s_nop 0
	v_mul_f32_e32 v33, v15, v33
	v_div_scale_f32 v0, s[0:1], v32, v32, v13
	v_rcp_f32_e32 v4, v0
	s_nop 0
	v_fma_f32 v8, -v0, v4, 1.0
	v_fmac_f32_e32 v4, v8, v4
	v_div_scale_f32 v8, vcc, v13, v32, v13
	v_mul_f32_e32 v15, v8, v4
	v_fma_f32 v24, -v0, v15, v8
	v_fmac_f32_e32 v15, v24, v4
	v_fma_f32 v0, -v0, v15, v8
	v_div_fmas_f32 v0, v0, v4, v15
	v_div_fixup_f32 v32, v0, v32, v13
	v_pk_fma_f32 v[34:35], v[14:15], v[38:39], v[34:35] op_sel_hi:[0,1,1]
	v_lshlrev_b32_e32 v13, 16, v25
	v_and_b32_e32 v15, 0xffff0000, v25
	v_pk_mul_f32 v[32:33], v[32:33], v[34:35]
	v_mul_f32_e32 v4, 0xbfb8aa3b, v13
	v_and_b32_e32 v25, 0xffff0000, v1
	v_lshlrev_b32_e32 v8, 16, v1
	v_mul_f32_e32 v1, 0xbfb8aa3b, v15
	v_cvt_pk_bf16_f32 v0, v32, v33
	v_exp_f32_e32 v4, v4
	v_lshlrev_b32_e32 v32, 16, v5
	v_and_b32_e32 v33, 0xffff0000, v5
	v_exp_f32_e32 v5, v1
	v_lshlrev_b32_e32 v24, 16, v9
	v_and_b32_e32 v9, 0xffff0000, v9
	v_pk_mul_f32 v[8:9], v[28:29], v[8:9] op_sel:[1,0] op_sel_hi:[0,1]
	v_pk_add_f32 v[4:5], v[4:5], 1.0 op_sel_hi:[1,0]
	v_pk_fma_f32 v[8:9], v[28:29], v[24:25], v[8:9]
	v_lshlrev_b32_e32 v24, 16, v2
	v_and_b32_e32 v25, 0xffff0000, v10
	v_pk_mul_f32 v[24:25], v[28:29], v[24:25] op_sel:[1,0] op_sel_hi:[0,1]
	v_rcp_f32_e32 v5, v5
	s_nop 0
	v_mul_f32_e32 v5, v15, v5
	v_div_scale_f32 v1, s[0:1], v4, v4, v13
	v_rcp_f32_e32 v15, v1
	s_nop 0
	v_fma_f32 v30, -v1, v15, 1.0
	v_fmac_f32_e32 v15, v30, v15
	v_div_scale_f32 v30, vcc, v13, v4, v13
	v_mul_f32_e32 v34, v30, v15
	v_fma_f32 v35, -v1, v34, v30
	v_fmac_f32_e32 v34, v35, v15
	v_fma_f32 v1, -v1, v34, v30
	v_div_fmas_f32 v1, v1, v15, v34
	v_div_fixup_f32 v4, v1, v4, v13
	v_pk_fma_f32 v[8:9], v[14:15], v[32:33], v[8:9] op_sel_hi:[0,1,1]
	v_pk_mul_f32 v[4:5], v[4:5], v[8:9]
	v_lshlrev_b32_e32 v13, 16, v26
	v_and_b32_e32 v15, 0xffff0000, v26
	v_cvt_pk_bf16_f32 v1, v4, v5
	v_mul_f32_e32 v4, 0xbfb8aa3b, v13
	v_and_b32_e32 v9, 0xffff0000, v2
	v_mul_f32_e32 v2, 0xbfb8aa3b, v15
	v_exp_f32_e32 v4, v4
	v_exp_f32_e32 v5, v2
	v_lshlrev_b32_e32 v32, 16, v6
	v_and_b32_e32 v33, 0xffff0000, v6
	v_lshlrev_b32_e32 v8, 16, v10
	v_pk_add_f32 v[4:5], v[4:5], 1.0 op_sel_hi:[1,0]
	v_pk_fma_f32 v[8:9], v[28:29], v[8:9], v[24:25]
	s_nop 0
	v_rcp_f32_e32 v5, v5
	s_nop 0
	v_mul_f32_e32 v5, v15, v5
	v_div_scale_f32 v2, s[0:1], v4, v4, v13
	v_rcp_f32_e32 v6, v2
	s_nop 0
	v_fma_f32 v10, -v2, v6, 1.0
	v_fmac_f32_e32 v6, v10, v6
	v_div_scale_f32 v10, vcc, v13, v4, v13
	v_mul_f32_e32 v15, v10, v6
	v_fma_f32 v26, -v2, v15, v10
	v_fmac_f32_e32 v15, v26, v6
	v_fma_f32 v2, -v2, v15, v10
	v_div_fmas_f32 v2, v2, v6, v15
	v_div_fixup_f32 v4, v2, v4, v13
	v_pk_fma_f32 v[8:9], v[14:15], v[32:33], v[8:9] op_sel_hi:[0,1,1]
	v_pk_mul_f32 v[4:5], v[4:5], v[8:9]
	v_lshlrev_b32_e32 v13, 16, v27
	v_and_b32_e32 v15, 0xffff0000, v27
	v_cvt_pk_bf16_f32 v2, v4, v5
	v_mul_f32_e32 v4, 0xbfb8aa3b, v13
	v_and_b32_e32 v9, 0xffff0000, v3
	v_lshlrev_b32_e32 v10, 16, v3
	v_mul_f32_e32 v3, 0xbfb8aa3b, v15
	v_exp_f32_e32 v4, v4
	v_exp_f32_e32 v5, v3
	v_lshlrev_b32_e32 v8, 16, v11
	v_and_b32_e32 v11, 0xffff0000, v11
	v_pk_mul_f32 v[10:11], v[28:29], v[10:11] op_sel:[1,0] op_sel_hi:[0,1]
	v_pk_add_f32 v[4:5], v[4:5], 1.0 op_sel_hi:[1,0]
; DI float lo16(unsigned w) { return __uint_as_float(w << 16); }
; DI float hi16(unsigned w) { return __uint_as_float(w & 0xffff0000u); }
; DI float siluf_(float x) { return x / (1.f + __expf(-x)); }
; DI void dilcomb_item(const Params& p, int it) {
;     ...
;     const float l0 = lse[((size_t)0 * T_ + tok) * 4 + h], l1 = lse[((size_t)1 * T_ + tok) * 4 + h], l2 = lse[((size_t)2 * T_ + tok) * 4 + h];
;     const float mx = fmaxf(l0, fmaxf(l1, l2));
;     float w0 = __expf(l0 - mx), w1 = __expf(l1 - mx), w2 = __expf(l2 - mx);
;     const float iw = 1.f / (w0 + w1 + w2); w0 *= iw; w1 *= iw; w2 *= iw;
;     const u32x4 a = *(const u32x4*)(od + ((size_t)0 * T_ + tok) * 256 + c8 * 8), bq = *(const u32x4*)(od + ((size_t)1 * T_ + tok) * 256 + c8 * 8), cq = *(const u32x4*)(od + ((size_t)2 * T_ + tok) * 256 + c8 * 8);
;     const u32x4 z = *(const u32x4*)(proj + tok * NP + C_BZ + c8 * 8);
;     u32x4 r;
; #pragma unroll
;     for (int e = 0; e < 4; ++e) {
;       const float v0 = (w0 * lo16(a[e]) + w1 * lo16(bq[e]) + w2 * lo16(cq[e])) * siluf_(lo16(z[e]));
;       const float v1 = (w0 * hi16(a[e]) + w1 * hi16(bq[e]) + w2 * hi16(cq[e])) * siluf_(hi16(z[e]));
;       r[e] = pk2(v0, v1);
;     }
;     *(u32x4*)(y + tok * 1024 + 256 + c8 * 8) = r;
;   }
; __global__ void __launch_bounds__(256, 2) hybrid_megakernel(Params p) {
;     ...
;       for (int k = 0; k < mine; ++k) { const int slot = start + k; sgu_item(p, l, slot * 8 + x, lds); pool_item(p, l, slot * 8 + x, lds); dilcomb_item(p, x * 64 + slot); }
	v_pk_fma_f32 v[8:9], v[28:29], v[8:9], v[10:11]
	v_lshlrev_b32_e32 v6, 16, v7
	v_and_b32_e32 v7, 0xffff0000, v7
	v_pk_fma_f32 v[6:7], v[14:15], v[6:7], v[8:9] op_sel_hi:[0,1,1]
	s_nop 0
	v_rcp_f32_e32 v5, v5
	s_nop 0
	v_mul_f32_e32 v5, v15, v5
	s_nop 0
	v_rcp_f32_e32 v4, v4
	s_nop 0
	v_mul_f32_e32 v4, v13, v4
	v_pk_mul_f32 v[4:5], v[4:5], v[6:7]
	s_nop 0
	v_cvt_pk_bf16_f32 v3, v4, v5
	v_mad_i64_i32 v[4:5], s[0:1], v12, s37, v[22:23]
	v_lshl_add_u64 v[4:5], v[4:5], 0, v[184:185]
	v_add_co_u32_e32 v4, vcc, s74, v4
	s_nop 1
	v_addc_co_u32_e32 v5, vcc, 0, v5, vcc
	global_store_dwordx4 v[4:5], v[0:3], off offset:512
	s_nop 1
	v_add_u32_e32 v0, 0x300, v31
	v_ashrrev_i32_e32 v22, 5, v0
	v_ashrrev_i32_e32 v23, 31, v22
	v_lshl_add_u64 v[0:1], v[22:23], 4, v[18:19]
	v_lshl_add_u64 v[4:5], v[22:23], 0, s[96:97]
	v_mov_b32_e32 v2, v156
	v_lshl_add_u64 v[0:1], v[4:5], 4, v[18:19]
	v_lshl_add_u64 v[6:7], v[22:23], 0, s[4:5]
	v_mov_b32_e32 v3, v157
	v_lshl_add_u64 v[0:1], v[6:7], 4, v[18:19]
	v_mov_b32_e32 v0, v158
	v_lshlrev_b64 v[4:5], 9, v[4:5]
	v_lshl_add_u64 v[4:5], v[16:17], 0, v[4:5]
	v_max3_f32 v1, v2, v3, v0
	v_sub_f32_e32 v2, v2, v1
	v_mul_f32_e32 v2, 0x3fb8aa3b, v2
	v_exp_f32_e32 v25, v2
	v_sub_f32_e32 v2, v3, v1
	v_mul_f32_e32 v2, 0x3fb8aa3b, v2
	v_sub_f32_e32 v0, v0, v1
	v_exp_f32_e32 v24, v2
	v_mul_f32_e32 v0, 0x3fb8aa3b, v0
	v_exp_f32_e32 v0, v0
	v_add_f32_e32 v1, v25, v24
	v_add_f32_e32 v1, v0, v1
	s_nop 0
	v_rcp_f32_e32 v26, v1
	s_nop 0
	v_mul_f32_e32 v18, v0, v26
	v_lshlrev_b64 v[0:1], 9, v[22:23]
	v_lshl_add_u64 v[0:1], v[16:17], 0, v[0:1]
	v_mov_b32_e32 v0, v128
	v_mov_b32_e32 v1, v129
	v_mov_b32_e32 v2, v130
	v_mov_b32_e32 v3, v131
	s_nop 0
	v_mov_b32_e32 v8, v132
	v_mov_b32_e32 v9, v133
	v_mov_b32_e32 v10, v134
	v_mov_b32_e32 v11, v135
	v_lshlrev_b64 v[4:5], 9, v[6:7]
	v_lshl_add_u64 v[4:5], v[16:17], 0, v[4:5]
	v_mad_i64_i32 v[16:17], s[0:1], v22, s33, v[20:21]
	v_lshl_add_u64 v[12:13], v[16:17], 0, v[184:185]
	v_add_co_u32_e32 v12, vcc, s93, v12
	v_mov_b32_e32 v4, v136
	v_mov_b32_e32 v5, v137
	v_mov_b32_e32 v6, v138
	v_mov_b32_e32 v7, v139
	s_nop 0
	v_addc_co_u32_e32 v13, vcc, 0, v13, vcc
	v_mov_b32_e32 v12, v140
	v_mov_b32_e32 v13, v141
	v_mov_b32_e32 v14, v142
	v_mov_b32_e32 v15, v143
	v_pk_mul_f32 v[20:21], v[24:25], v[26:27] op_sel_hi:[1,0]
	v_and_b32_e32 v27, 0xffff0000, v0
	v_lshlrev_b32_e32 v28, 16, v0
	v_lshlrev_b32_e32 v26, 16, v8
	v_and_b32_e32 v29, 0xffff0000, v8
	v_pk_mul_f32 v[28:29], v[20:21], v[28:29] op_sel:[1,0] op_sel_hi:[0,1]
	v_pk_fma_f32 v[26:27], v[20:21], v[26:27], v[28:29]
	v_lshlrev_b32_e32 v30, 16, v4
	v_and_b32_e32 v31, 0xffff0000, v4
	v_lshlrev_b32_e32 v19, 16, v12
	v_and_b32_e32 v12, 0xffff0000, v12
	v_mul_f32_e32 v23, 0xbfb8aa3b, v19
	v_mul_f32_e32 v0, 0xbfb8aa3b, v12
	v_exp_f32_e32 v24, v23
	v_exp_f32_e32 v25, v0
	v_pk_fma_f32 v[26:27], v[18:19], v[30:31], v[26:27] op_sel_hi:[0,1,1]
	v_pk_add_f32 v[24:25], v[24:25], 1.0 op_sel_hi:[1,0]
	s_nop 0
	s_nop 0
	v_rcp_f32_e32 v25, v25
	s_nop 0
	v_mul_f32_e32 v25, v12, v25
	s_nop 0
	v_rcp_f32_e32 v24, v24
	s_nop 0
	v_mul_f32_e32 v24, v19, v24
	v_lshlrev_b32_e32 v19, 16, v13
	v_and_b32_e32 v23, 0xffff0000, v13
	v_pk_mul_f32 v[24:25], v[24:25], v[26:27]
	v_mul_f32_e32 v4, 0xbfb8aa3b, v19
	v_and_b32_e32 v13, 0xffff0000, v1
	v_lshlrev_b32_e32 v8, 16, v1
	v_mul_f32_e32 v1, 0xbfb8aa3b, v23
	v_cvt_pk_bf16_f32 v0, v24, v25
	v_exp_f32_e32 v4, v4
	v_lshlrev_b32_e32 v24, 16, v5
	v_and_b32_e32 v25, 0xffff0000, v5
	v_exp_f32_e32 v5, v1
	v_lshlrev_b32_e32 v12, 16, v9
	v_and_b32_e32 v9, 0xffff0000, v9
	v_pk_mul_f32 v[8:9], v[20:21], v[8:9] op_sel:[1,0] op_sel_hi:[0,1]
	v_pk_add_f32 v[4:5], v[4:5], 1.0 op_sel_hi:[1,0]
	v_pk_fma_f32 v[8:9], v[20:21], v[12:13], v[8:9]
	v_pk_fma_f32 v[8:9], v[18:19], v[24:25], v[8:9] op_sel_hi:[0,1,1]
	v_lshlrev_b32_e32 v12, 16, v2
	v_lshlrev_b32_e32 v24, 16, v6
	v_rcp_f32_e32 v5, v5
	s_nop 0
	v_mul_f32_e32 v5, v23, v5
	v_and_b32_e32 v25, 0xffff0000, v6
	v_and_b32_e32 v13, 0xffff0000, v10
	v_pk_mul_f32 v[12:13], v[20:21], v[12:13] op_sel:[1,0] op_sel_hi:[0,1]
	v_rcp_f32_e32 v4, v4
	s_nop 0
	v_mul_f32_e32 v4, v19, v4
	v_pk_mul_f32 v[4:5], v[4:5], v[8:9]
	v_lshlrev_b32_e32 v19, 16, v14
	v_and_b32_e32 v14, 0xffff0000, v14
	v_cvt_pk_bf16_f32 v1, v4, v5
	v_mul_f32_e32 v4, 0xbfb8aa3b, v19
	v_and_b32_e32 v9, 0xffff0000, v2
	v_mul_f32_e32 v2, 0xbfb8aa3b, v14
	v_exp_f32_e32 v4, v4
	v_exp_f32_e32 v5, v2
	v_lshlrev_b32_e32 v8, 16, v10
	v_pk_fma_f32 v[8:9], v[20:21], v[8:9], v[12:13]
	v_lshlrev_b32_e32 v12, 16, v15
	v_pk_add_f32 v[4:5], v[4:5], 1.0 op_sel_hi:[1,0]
	v_pk_fma_f32 v[8:9], v[18:19], v[24:25], v[8:9] op_sel_hi:[0,1,1]
	v_and_b32_e32 v13, 0xffff0000, v15
	v_rcp_f32_e32 v5, v5
	s_nop 0
	v_mul_f32_e32 v5, v14, v5
	s_nop 0
	v_rcp_f32_e32 v4, v4
	s_nop 0
	v_mul_f32_e32 v4, v19, v4
	v_pk_mul_f32 v[4:5], v[4:5], v[8:9]
	v_and_b32_e32 v9, 0xffff0000, v3
	v_cvt_pk_bf16_f32 v2, v4, v5
	v_mul_f32_e32 v4, 0xbfb8aa3b, v12
	v_lshlrev_b32_e32 v10, 16, v3
	v_mul_f32_e32 v3, 0xbfb8aa3b, v13
	v_exp_f32_e32 v4, v4
	v_exp_f32_e32 v5, v3
	v_lshlrev_b32_e32 v8, 16, v11
	v_and_b32_e32 v11, 0xffff0000, v11
	v_pk_mul_f32 v[10:11], v[20:21], v[10:11] op_sel:[1,0] op_sel_hi:[0,1]
	v_pk_add_f32 v[4:5], v[4:5], 1.0 op_sel_hi:[1,0]
	v_pk_fma_f32 v[8:9], v[20:21], v[8:9], v[10:11]
	v_lshlrev_b32_e32 v6, 16, v7
	v_and_b32_e32 v7, 0xffff0000, v7
	v_pk_fma_f32 v[6:7], v[18:19], v[6:7], v[8:9] op_sel_hi:[0,1,1]
	s_nop 0
	v_rcp_f32_e32 v5, v5
	s_nop 0
	v_mul_f32_e32 v5, v13, v5
	s_nop 0
	v_rcp_f32_e32 v4, v4
	s_nop 0
	v_mul_f32_e32 v4, v12, v4
	v_pk_mul_f32 v[4:5], v[4:5], v[6:7]
	s_nop 0
	v_cvt_pk_bf16_f32 v3, v4, v5
	v_mad_i64_i32 v[4:5], s[0:1], v22, s37, v[16:17]
	v_lshl_add_u64 v[4:5], v[4:5], 0, v[184:185]
	v_add_co_u32_e32 v4, vcc, 0x2a40000, v4
	s_nop 1
	v_addc_co_u32_e32 v5, vcc, 0, v5, vcc
	v_cmp_eq_u32_e32 vcc, s6, v116
	global_store_dwordx4 v[4:5], v[0:3], off offset:512
	s_cbranch_vccz .LBB0_411
	s_branch .LBB0_345
